# GEMM prologues: early wait-for-all dropped in all ten; 3-stage merge loops: last k-step no longer waits for the loads past the end of K
# speedup vs baseline: 1.0430x; 1.0011x over previous
.LBB0_126:
	s_and_b32 s2, s30, 7
	s_lshl_b32 s2, s2, 18
	s_add_i32 s2, s35, s2
	s_lshl_b32 s10, s2, 1
	s_and_b32 s2, s43, 7
	v_mov_b32_e32 v24, v198
	s_or_b32 s9, s2, s69
	s_ashr_i32 s8, s43, 3
	s_lshl_b32 s2, s8, 8
	v_ashrrev_i32_e32 v25, 6, v24
	v_bfe_u32 v0, v24, 3, 3
	s_lshl_b32 s3, s9, 19
	v_lshl_or_b32 v0, v25, 3, v0
	s_add_u32 s6, s1, s3
	v_lshrrev_b32_e32 v27, 1, v0
	s_addc_u32 s7, s19, 0
	s_ashr_i32 s3, s2, 31
	v_xor_b32_e32 v6, v27, v24
	v_ashrrev_i32_e32 v1, 31, v0
	s_lshl_b64 s[4:5], s[2:3], 11
	v_lshlrev_b64 v[2:3], 11, v[0:1]
	v_lshlrev_b32_e32 v1, 4, v6
	v_add_u32_e32 v6, 64, v0
	v_add_u32_e32 v10, 0x80, v0
	v_add_u32_e32 v0, 0xc0, v0
	s_add_u32 s20, s28, s4
	v_and_b32_e32 v136, 0x70, v1
	v_ashrrev_i32_e32 v7, 31, v6
	v_ashrrev_i32_e32 v11, 31, v10
	v_ashrrev_i32_e32 v1, 31, v0
	s_addc_u32 s21, s29, s5
	v_lshlrev_b64 v[6:7], 11, v[6:7]
	v_lshlrev_b64 v[10:11], 11, v[10:11]
	v_lshlrev_b64 v[0:1], 11, v[0:1]
	v_lshl_add_u64 v[4:5], s[6:7], 0, v[2:3]
	v_lshl_add_u64 v[8:9], s[6:7], 0, v[6:7]
	v_lshl_add_u64 v[12:13], s[6:7], 0, v[10:11]
	v_lshl_add_u64 v[14:15], s[6:7], 0, v[0:1]
	v_lshl_add_u64 v[16:17], s[20:21], 0, v[2:3]
	v_lshl_add_u64 v[18:19], s[20:21], 0, v[6:7]
	v_lshl_add_u64 v[20:21], s[20:21], 0, v[10:11]
	v_lshl_add_u64 v[22:23], s[20:21], 0, v[0:1]
	v_lshl_add_u64 v[4:5], v[4:5], 0, v[136:137]
	v_lshl_add_u64 v[8:9], v[8:9], 0, v[136:137]
	v_lshl_add_u64 v[12:13], v[12:13], 0, v[136:137]
	v_lshl_add_u64 v[14:15], v[14:15], 0, v[136:137]
	v_lshl_add_u64 v[16:17], v[16:17], 0, v[136:137]
	v_lshl_add_u64 v[18:19], v[18:19], 0, v[136:137]
	v_lshl_add_u64 v[20:21], v[20:21], 0, v[136:137]
	v_lshl_add_u64 v[22:23], v[22:23], 0, v[136:137]
	v_lshl_add_u32 v136, v25, 10, 0
	v_bfe_u32 v28, v24, 4, 2
	v_readfirstlane_b32 s3, v136
	s_mov_b32 m0, s3
	v_bfe_u32 v29, v24, 1, 3
	global_load_lds_dwordx4 v[4:5], off
	v_add_u32_e32 v4, 0x2000, v136
	s_add_u32 s6, s31, s10
	v_readfirstlane_b32 s3, v4
	v_add_u32_e32 v4, 0x4000, v136
	s_mov_b32 m0, s3
	v_readfirstlane_b32 s3, v4
	v_add_u32_e32 v4, 0x6000, v136
	global_load_lds_dwordx4 v[8:9], off
	s_mov_b32 m0, s3
	v_readfirstlane_b32 s3, v4
	v_add_u32_e32 v4, 0x8000, v136
	global_load_lds_dwordx4 v[12:13], off
	s_mov_b32 m0, s3
	v_readfirstlane_b32 s3, v4
	v_add_u32_e32 v4, 0xa000, v136
	global_load_lds_dwordx4 v[14:15], off
	s_mov_b32 m0, s3
	v_readfirstlane_b32 s3, v4
	v_add_u32_e32 v4, 0xc000, v136
	global_load_lds_dwordx4 v[16:17], off
	s_mov_b32 m0, s3
	v_readfirstlane_b32 s3, v4
	v_add_u32_e32 v4, 0xe000, v136
	global_load_lds_dwordx4 v[18:19], off
	s_mov_b32 m0, s3
	v_readfirstlane_b32 s3, v4
	global_load_lds_dwordx4 v[20:21], off
	s_mov_b32 m0, s3
	v_lshrrev_b32_e32 v4, 30, v25
	global_load_lds_dwordx4 v[22:23], off
	v_add_u32_e32 v4, v25, v4
	v_ashrrev_i32_e32 v4, 2, v4
	v_mul_i32_i24_e32 v5, 4, v4
	v_lshlrev_b32_e32 v151, 14, v4
	v_xor_b32_e32 v4, v28, v29
	v_lshlrev_b32_e32 v152, 4, v4
	v_bitop3_b32 v4, v28, v29, 4 bitop3:0x36
	v_lshlrev_b32_e32 v153, 4, v4
	v_bitop3_b32 v4, v27, 7, v24 bitop3:0x48
	s_addc_u32 s7, s34, 0
	v_lshlrev_b32_e32 v4, 4, v4
	s_add_u32 s4, s36, s4
	v_and_b32_e32 v26, 15, v24
	v_sub_u32_e32 v5, v25, v5
	v_or_b32_e32 v2, v2, v4
	v_or_b32_e32 v6, v6, v4
	v_or_b32_e32 v10, v10, v4
	v_or_b32_e32 v0, v0, v4
	s_addc_u32 s5, s37, s5
	v_lshlrev_b32_e32 v149, 13, v5
	v_lshlrev_b32_e32 v150, 7, v26
	v_lshl_add_u64 v[128:129], s[6:7], 0, v[2:3]
	v_lshl_add_u64 v[130:131], s[6:7], 0, v[6:7]
	v_lshl_add_u64 v[132:133], s[6:7], 0, v[10:11]
	v_lshl_add_u64 v[134:135], s[6:7], 0, v[0:1]
	v_lshl_add_u64 v[138:139], s[4:5], 0, v[2:3]
	v_lshl_add_u64 v[140:141], s[4:5], 0, v[6:7]
	v_lshl_add_u64 v[142:143], s[4:5], 0, v[10:11]
	v_lshl_add_u64 v[144:145], s[4:5], 0, v[0:1]
	s_mov_b32 s3, 0
	s_mov_b64 s[4:5], 0
	v_mov_b32_e32 v12, 0
	v_mov_b32_e32 v13, v137
	v_mov_b32_e32 v14, v137
	v_mov_b32_e32 v15, v137
	v_mov_b32_e32 v8, 0
	v_mov_b32_e32 v9, v137
	v_mov_b32_e32 v10, v137
	v_mov_b32_e32 v11, v137
	v_mov_b32_e32 v0, 0
	v_mov_b32_e32 v1, v137
	v_mov_b32_e32 v2, v137
	v_mov_b32_e32 v3, v137
	v_mov_b32_e32 v4, 0
	v_mov_b32_e32 v5, v137
	v_mov_b32_e32 v6, v137
	v_mov_b32_e32 v7, v137
	v_mov_b32_e32 v16, 0
	v_mov_b32_e32 v17, v137
	v_mov_b32_e32 v18, v137
	v_mov_b32_e32 v19, v137
	v_mov_b32_e32 v28, 0
	v_mov_b32_e32 v29, v137
	v_mov_b32_e32 v30, v137
	v_mov_b32_e32 v31, v137
	v_mov_b32_e32 v20, 0
	v_mov_b32_e32 v21, v137
	v_mov_b32_e32 v22, v137
	v_mov_b32_e32 v23, v137
	v_mov_b32_e32 v24, 0
	v_mov_b32_e32 v25, v137
	v_mov_b32_e32 v26, v137
	v_mov_b32_e32 v27, v137
	v_mov_b32_e32 v32, 0
	v_mov_b32_e32 v33, v137
	v_mov_b32_e32 v34, v137
	v_mov_b32_e32 v35, v137
	v_mov_b32_e32 v44, 0
	v_mov_b32_e32 v45, v137
	v_mov_b32_e32 v46, v137
	v_mov_b32_e32 v47, v137
	v_mov_b32_e32 v36, 0
	v_mov_b32_e32 v37, v137
	v_mov_b32_e32 v38, v137
	v_mov_b32_e32 v39, v137
	v_mov_b32_e32 v40, 0
	v_mov_b32_e32 v41, v137
	v_mov_b32_e32 v42, v137
	v_mov_b32_e32 v43, v137
	v_mov_b32_e32 v48, 0
	v_mov_b32_e32 v49, v137
	v_mov_b32_e32 v50, v137
	v_mov_b32_e32 v51, v137
	v_mov_b32_e32 v60, 0
	v_mov_b32_e32 v61, v137
	v_mov_b32_e32 v62, v137
	v_mov_b32_e32 v63, v137
	v_mov_b32_e32 v52, 0
	v_mov_b32_e32 v53, v137
	v_mov_b32_e32 v54, v137
	v_mov_b32_e32 v55, v137
	v_mov_b32_e32 v56, 0
	v_mov_b32_e32 v57, v137
	v_mov_b32_e32 v58, v137
	v_mov_b32_e32 v59, v137
	v_mov_b32_e32 v64, 0
	v_mov_b32_e32 v65, v137
	v_mov_b32_e32 v66, v137
	v_mov_b32_e32 v67, v137
	v_mov_b32_e32 v76, 0
	v_mov_b32_e32 v77, v137
	v_mov_b32_e32 v78, v137
	v_mov_b32_e32 v79, v137
	v_mov_b32_e32 v68, 0
	v_mov_b32_e32 v69, v137
	v_mov_b32_e32 v70, v137
	v_mov_b32_e32 v71, v137
	v_mov_b32_e32 v72, 0
	v_mov_b32_e32 v73, v137
	v_mov_b32_e32 v74, v137
	v_mov_b32_e32 v75, v137
	v_mov_b32_e32 v80, 0
	v_mov_b32_e32 v81, v137
	v_mov_b32_e32 v82, v137
	v_mov_b32_e32 v83, v137
	v_mov_b32_e32 v92, 0
	v_mov_b32_e32 v93, v137
	v_mov_b32_e32 v94, v137
	v_mov_b32_e32 v95, v137
	v_mov_b32_e32 v84, 0
	v_mov_b32_e32 v85, v137
	v_mov_b32_e32 v86, v137
	v_mov_b32_e32 v87, v137
	v_mov_b32_e32 v88, 0
	v_mov_b32_e32 v89, v137
	v_mov_b32_e32 v90, v137
	v_mov_b32_e32 v91, v137
	v_mov_b32_e32 v96, 0
	v_mov_b32_e32 v97, v137
	v_mov_b32_e32 v98, v137
	v_mov_b32_e32 v99, v137
	v_mov_b32_e32 v108, 0
	v_mov_b32_e32 v109, v137
	v_mov_b32_e32 v110, v137
	v_mov_b32_e32 v111, v137
	v_mov_b32_e32 v100, 0
	v_mov_b32_e32 v101, v137
	v_mov_b32_e32 v102, v137
	v_mov_b32_e32 v103, v137
	v_mov_b32_e32 v104, 0
	v_mov_b32_e32 v105, v137
	v_mov_b32_e32 v106, v137
	v_mov_b32_e32 v107, v137
	v_mov_b32_e32 v112, 0
	v_mov_b32_e32 v113, v137
	v_mov_b32_e32 v114, v137
	v_mov_b32_e32 v115, v137
	v_mov_b32_e32 v124, 0
	v_mov_b32_e32 v125, v137
	v_mov_b32_e32 v126, v137
	v_mov_b32_e32 v127, v137
	v_mov_b32_e32 v116, 0
	v_mov_b32_e32 v117, v137
	v_mov_b32_e32 v118, v137
	v_mov_b32_e32 v119, v137
	v_mov_b32_e32 v120, 0
	v_mov_b32_e32 v121, v137
	v_mov_b32_e32 v122, v137
	v_mov_b32_e32 v123, v137
	s_waitcnt vmcnt(0) lgkmcnt(0)
	s_barrier
	s_branch .LBB0_128

.LBB0_384:
	v_cmp_lt_i32_e32 vcc, 7, v0
	s_and_saveexec_b64 s[2:3], vcc
	s_xor_b64 s[70:71], exec, s[2:3]
	s_cbranch_execz .LBB0_580
	v_cmp_lt_u32_e32 vcc, 15, v0
	s_and_saveexec_b64 s[2:3], vcc
	s_xor_b64 s[72:73], exec, s[2:3]
	s_cbranch_execz .LBB0_571
	v_cmp_lt_u32_e32 vcc, 23, v0
	s_and_saveexec_b64 s[2:3], vcc
	s_xor_b64 s[64:65], exec, s[2:3]
	s_cbranch_execz .LBB0_566
	v_cmp_lt_u32_e32 vcc, 55, v0
	s_and_saveexec_b64 s[2:3], vcc
	s_xor_b64 s[4:5], exec, s[2:3]
	s_cbranch_execz .LBB0_459
	v_readlane_b32 s2, v240, 24
	v_mov_b32_e32 v36, v198
	v_and_b32_e32 v148, 3, v0
	v_add_u32_e32 v1, s2, v0
	v_lshrrev_b32_e32 v149, 2, v1
	s_mov_b32 s2, 0x142000
	v_mul_lo_u32 v168, v149, s2
	v_ashrrev_i32_e32 v37, 6, v36
	v_bfe_u32 v6, v36, 3, 3
	v_lshlrev_b64 v[0:1], 1, v[168:169]
	v_lshl_or_b32 v6, v37, 3, v6
	v_lshl_add_u64 v[2:3], s[62:63], 0, v[0:1]
	s_mov_b64 s[2:3], 0x38e1600
	v_lshrrev_b32_e32 v39, 1, v6
	v_lshl_add_u64 v[2:3], v[2:3], 0, s[2:3]
	v_xor_b32_e32 v10, v39, v36
	v_add_u32_e32 v12, 64, v6
	v_add_u32_e32 v16, 0x80, v6
	v_add_u32_e32 v20, 0xc0, v6
	v_mad_i64_i32 v[8:9], s[2:3], v6, s59, v[2:3]
	v_lshlrev_b32_e32 v10, 4, v10
	v_mad_i64_i32 v[14:15], s[2:3], v12, s59, v[2:3]
	v_mad_i64_i32 v[18:19], s[2:3], v16, s59, v[2:3]
	v_mad_i64_i32 v[2:3], s[2:3], v20, s59, v[2:3]
	v_lshl_add_u32 v150, v37, 10, 0
	v_and_b32_e32 v10, 0x70, v10
	v_mov_b32_e32 v11, v169
	v_readfirstlane_b32 s2, v150
	v_lshl_add_u64 v[8:9], v[8:9], 0, v[10:11]
	s_mov_b32 m0, s2
	v_lshl_add_u64 v[14:15], v[14:15], 0, v[10:11]
	global_load_lds_dwordx4 v[8:9], off
	v_add_u32_e32 v8, 0x2000, v150
	v_lshl_add_u64 v[18:19], v[18:19], 0, v[10:11]
	v_readfirstlane_b32 s2, v8
	v_add_u32_e32 v8, 0x4000, v150
	s_mov_b32 m0, s2
	v_readfirstlane_b32 s2, v8
	v_add_u32_e32 v8, 0x6000, v150
	global_load_lds_dwordx4 v[14:15], off
	s_mov_b32 m0, s2
	v_readfirstlane_b32 s2, v8
	v_lshlrev_b32_e32 v168, 17, v148
	v_ashrrev_i32_e32 v7, 31, v6
	v_lshl_add_u64 v[2:3], v[2:3], 0, v[10:11]
	global_load_lds_dwordx4 v[18:19], off
	s_mov_b32 m0, s2
	v_lshl_add_u64 v[4:5], s[12:13], 0, v[168:169]
	v_ashrrev_i32_e32 v13, 31, v12
	v_lshlrev_b64 v[22:23], 9, v[6:7]
	global_load_lds_dwordx4 v[2:3], off
	v_add_u32_e32 v2, 0x8000, v150
	v_ashrrev_i32_e32 v17, 31, v16
	v_lshl_add_u64 v[24:25], v[4:5], 0, v[22:23]
	v_lshlrev_b64 v[26:27], 9, v[12:13]
	v_readfirstlane_b32 s2, v2
	v_add_u32_e32 v2, 0xa000, v150
	v_ashrrev_i32_e32 v21, 31, v20
	v_lshl_add_u64 v[24:25], v[24:25], 0, v[10:11]
	v_lshl_add_u64 v[28:29], v[4:5], 0, v[26:27]
	v_lshlrev_b64 v[30:31], 9, v[16:17]
	s_mov_b32 m0, s2
	v_readfirstlane_b32 s2, v2
	v_add_u32_e32 v2, 0xc000, v150
	v_lshl_add_u64 v[28:29], v[28:29], 0, v[10:11]
	v_lshl_add_u64 v[32:33], v[4:5], 0, v[30:31]
	v_lshlrev_b64 v[34:35], 9, v[20:21]
	global_load_lds_dwordx4 v[24:25], off
	s_mov_b32 m0, s2
	v_readfirstlane_b32 s2, v2
	v_add_u32_e32 v2, 0xe000, v150
	v_lshl_add_u64 v[32:33], v[32:33], 0, v[10:11]
	v_lshl_add_u64 v[4:5], v[4:5], 0, v[34:35]
	global_load_lds_dwordx4 v[28:29], off
	s_mov_b32 m0, s2
	v_readfirstlane_b32 s2, v2
	v_lshl_add_u64 v[4:5], v[4:5], 0, v[10:11]
	global_load_lds_dwordx4 v[32:33], off
	s_mov_b32 m0, s2
	v_lshrrev_b32_e32 v2, 30, v37
	global_load_lds_dwordx4 v[4:5], off
	v_add_u32_e32 v2, v37, v2
	v_bfe_u32 v7, v36, 4, 2
	v_bfe_u32 v10, v36, 1, 3
	v_ashrrev_i32_e32 v2, 2, v2
	v_mul_i32_i24_e32 v3, 4, v2
	v_lshlrev_b32_e32 v153, 14, v2
	v_xor_b32_e32 v2, v7, v10
	v_lshlrev_b32_e32 v154, 4, v2
	v_bitop3_b32 v2, v7, v10, 4 bitop3:0x36
	v_sub_u32_e32 v3, v37, v3
	v_lshlrev_b32_e32 v155, 4, v2
	v_bitop3_b32 v2, v39, 7, v36 bitop3:0x48
	v_lshlrev_b32_e32 v151, 13, v3
	v_lshlrev_b32_e32 v2, 4, v2
	v_mov_b32_e32 v3, v169
	v_mad_i64_i32 v[4:5], s[2:3], v6, s59, v[2:3]
	v_lshl_add_u64 v[4:5], v[4:5], 0, v[0:1]
	v_lshl_add_u64 v[132:133], s[38:39], 0, v[4:5]
	v_mad_i64_i32 v[4:5], s[2:3], v12, s59, v[2:3]
	v_lshl_add_u64 v[4:5], v[4:5], 0, v[0:1]
	v_lshl_add_u64 v[134:135], s[38:39], 0, v[4:5]
	v_mad_i64_i32 v[4:5], s[2:3], v16, s59, v[2:3]
	v_lshl_add_u64 v[4:5], v[4:5], 0, v[0:1]
	v_lshl_add_u64 v[136:137], s[38:39], 0, v[4:5]
	v_mad_i64_i32 v[4:5], s[2:3], v20, s59, v[2:3]
	v_lshl_add_u64 v[0:1], v[4:5], 0, v[0:1]
	v_lshl_add_u64 v[138:139], s[38:39], 0, v[0:1]
	v_lshl_add_u64 v[0:1], v[168:169], 0, v[22:23]
	v_or_b32_e32 v0, v0, v2
	v_lshl_add_u64 v[140:141], s[40:41], 0, v[0:1]
	v_lshl_add_u64 v[0:1], v[168:169], 0, v[26:27]
	v_or_b32_e32 v0, v0, v2
	v_lshl_add_u64 v[142:143], s[40:41], 0, v[0:1]
	v_lshl_add_u64 v[0:1], v[168:169], 0, v[30:31]
	v_or_b32_e32 v0, v0, v2
	v_lshl_add_u64 v[144:145], s[40:41], 0, v[0:1]
	v_lshl_add_u64 v[0:1], v[168:169], 0, v[34:35]
	v_and_b32_e32 v38, 15, v36
	v_or_b32_e32 v0, v0, v2
	v_mov_b32_e32 v4, 0
	v_lshlrev_b32_e32 v152, 7, v38
	v_lshl_add_u64 v[146:147], s[40:41], 0, v[0:1]
	s_mov_b32 s66, 0
	s_mov_b64 s[2:3], 0
	v_mov_b32_e32 v5, v4
	v_mov_b32_e32 v6, v4
	v_mov_b32_e32 v7, v4
	v_mov_b32_e32 v0, v4
	v_mov_b32_e32 v1, v4
	v_mov_b32_e32 v2, v4
	v_mov_b32_e32 v3, v4
	v_mov_b32_e32 v8, v4
	v_mov_b32_e32 v9, v4
	v_mov_b32_e32 v10, v4
	v_mov_b32_e32 v11, v4
	v_mov_b32_e32 v12, v4
	v_mov_b32_e32 v13, v4
	v_mov_b32_e32 v14, v4
	v_mov_b32_e32 v15, v4
	v_mov_b32_e32 v16, v4
	v_mov_b32_e32 v17, v4
	v_mov_b32_e32 v18, v4
	v_mov_b32_e32 v19, v4
	v_mov_b32_e32 v20, v4
	v_mov_b32_e32 v21, v4
	v_mov_b32_e32 v22, v4
	v_mov_b32_e32 v23, v4
	v_mov_b32_e32 v24, v4
	v_mov_b32_e32 v25, v4
	v_mov_b32_e32 v26, v4
	v_mov_b32_e32 v27, v4
	v_mov_b32_e32 v28, v4
	v_mov_b32_e32 v29, v4
	v_mov_b32_e32 v30, v4
	v_mov_b32_e32 v31, v4
	v_mov_b32_e32 v32, v4
	v_mov_b32_e32 v33, v4
	v_mov_b32_e32 v34, v4
	v_mov_b32_e32 v35, v4
	v_mov_b32_e32 v36, v4
	v_mov_b32_e32 v37, v4
	v_mov_b32_e32 v38, v4
	v_mov_b32_e32 v39, v4
	v_mov_b32_e32 v40, v4
	v_mov_b32_e32 v41, v4
	v_mov_b32_e32 v42, v4
	v_mov_b32_e32 v43, v4
	v_mov_b32_e32 v44, v4
	v_mov_b32_e32 v45, v4
	v_mov_b32_e32 v46, v4
	v_mov_b32_e32 v47, v4
	v_mov_b32_e32 v48, v4
	v_mov_b32_e32 v49, v4
	v_mov_b32_e32 v50, v4
	v_mov_b32_e32 v51, v4
	v_mov_b32_e32 v52, v4
	v_mov_b32_e32 v53, v4
	v_mov_b32_e32 v54, v4
	v_mov_b32_e32 v55, v4
	v_mov_b32_e32 v56, v4
	v_mov_b32_e32 v57, v4
	v_mov_b32_e32 v58, v4
	v_mov_b32_e32 v59, v4
	v_mov_b32_e32 v60, v4
	v_mov_b32_e32 v61, v4
	v_mov_b32_e32 v62, v4
	v_mov_b32_e32 v63, v4
	v_mov_b32_e32 v64, v4
	v_mov_b32_e32 v65, v4
	v_mov_b32_e32 v66, v4
	v_mov_b32_e32 v67, v4
	v_mov_b32_e32 v68, v4
	v_mov_b32_e32 v69, v4
	v_mov_b32_e32 v70, v4
	v_mov_b32_e32 v71, v4
	v_mov_b32_e32 v72, v4
	v_mov_b32_e32 v73, v4
	v_mov_b32_e32 v74, v4
	v_mov_b32_e32 v75, v4
	v_mov_b32_e32 v76, v4
	v_mov_b32_e32 v77, v4
	v_mov_b32_e32 v78, v4
	v_mov_b32_e32 v79, v4
	v_mov_b32_e32 v80, v4
	v_mov_b32_e32 v81, v4
	v_mov_b32_e32 v82, v4
	v_mov_b32_e32 v83, v4
	v_mov_b32_e32 v84, v4
	v_mov_b32_e32 v85, v4
	v_mov_b32_e32 v86, v4
	v_mov_b32_e32 v87, v4
	v_mov_b32_e32 v88, v4
	v_mov_b32_e32 v89, v4
	v_mov_b32_e32 v90, v4
	v_mov_b32_e32 v91, v4
	v_mov_b32_e32 v92, v4
	v_mov_b32_e32 v93, v4
	v_mov_b32_e32 v94, v4
	v_mov_b32_e32 v95, v4
	v_mov_b32_e32 v96, v4
	v_mov_b32_e32 v97, v4
	v_mov_b32_e32 v98, v4
	v_mov_b32_e32 v99, v4
	v_mov_b32_e32 v100, v4
	v_mov_b32_e32 v101, v4
	v_mov_b32_e32 v102, v4
	v_mov_b32_e32 v103, v4
	v_mov_b32_e32 v104, v4
	v_mov_b32_e32 v105, v4
	v_mov_b32_e32 v106, v4
	v_mov_b32_e32 v107, v4
	v_mov_b32_e32 v108, v4
	v_mov_b32_e32 v109, v4
	v_mov_b32_e32 v110, v4
	v_mov_b32_e32 v111, v4
	v_mov_b32_e32 v112, v4
	v_mov_b32_e32 v113, v4
	v_mov_b32_e32 v114, v4
	v_mov_b32_e32 v115, v4
	v_mov_b32_e32 v116, v4
	v_mov_b32_e32 v117, v4
	v_mov_b32_e32 v118, v4
	v_mov_b32_e32 v119, v4
	v_mov_b32_e32 v120, v4
	v_mov_b32_e32 v121, v4
	v_mov_b32_e32 v122, v4
	v_mov_b32_e32 v123, v4
	v_mov_b32_e32 v124, v4
	v_mov_b32_e32 v125, v4
	v_mov_b32_e32 v126, v4
	v_mov_b32_e32 v127, v4
	s_waitcnt vmcnt(0) lgkmcnt(0)
	s_barrier
	s_branch .LBB0_390

.Lg3a_gemm7:
	s_mul_i32 m0, m0, 0xc000
	s_add_i32 s54, s54, m0
	s_mul_i32 s53, s53, 0xc000
	s_add_i32 s53, s53, 0
	v_add3_u32 v147, s53, v142, v143
	v_add_u32_e32 v168, v147, v145
	v_add3_u32 v172, s53, v144, v143
	v_add_u32_e32 v173, v172, v145
	ds_read_b128 v[148:151], v168 offset:32768
	ds_read_b128 v[152:155], v168 offset:34816
	ds_read_b128 v[164:167], v168 offset:36864
	ds_read_b128 v[168:171], v168 offset:38912
	ds_read_b128 v[156:159], v173
	ds_read_b128 v[160:163], v173 offset:2048
	ds_read_b128 v[242:245], v173 offset:4096
	ds_read_b128 v[246:249], v173 offset:6144
	s_add_u32 s12, s12, 0x80
	s_addc_u32 s13, s13, 0
	s_mov_b32 m0, s54
	v_lshl_add_u64 v[254:255], v[130:131], 0, s[12:13]
	global_load_lds_dwordx4 v[254:255], off
	s_add_i32 m0, s54, 0x2000
	v_lshl_add_u64 v[254:255], v[132:133], 0, s[12:13]
	global_load_lds_dwordx4 v[254:255], off
	s_waitcnt lgkmcnt(2)
	v_mfma_f32_16x16x32_bf16 v[60:63], v[148:151], v[156:159], v[60:63]
	v_add_u32_e32 v147, v147, v146
	v_add_u32_e32 v172, v172, v146
	v_mfma_f32_16x16x32_bf16 v[44:47], v[148:151], v[160:163], v[44:47]
	v_mfma_f32_16x16x32_bf16 v[56:59], v[152:155], v[156:159], v[56:59]
	v_mfma_f32_16x16x32_bf16 v[40:43], v[152:155], v[160:163], v[40:43]
	s_add_i32 m0, s54, 0x4000
	v_lshl_add_u64 v[254:255], v[134:135], 0, s[12:13]
	global_load_lds_dwordx4 v[254:255], off
	v_mfma_f32_16x16x32_bf16 v[52:55], v[164:167], v[156:159], v[52:55]
	v_mfma_f32_16x16x32_bf16 v[36:39], v[164:167], v[160:163], v[36:39]
	v_mfma_f32_16x16x32_bf16 v[48:51], v[168:171], v[156:159], v[48:51]
	v_mfma_f32_16x16x32_bf16 v[32:35], v[168:171], v[160:163], v[32:35]
	s_add_i32 m0, s54, 0x6000
	v_lshl_add_u64 v[254:255], v[136:137], 0, s[12:13]
	global_load_lds_dwordx4 v[254:255], off
	ds_read_b128 v[156:159], v172
	ds_read_b128 v[160:163], v172 offset:2048
	s_waitcnt lgkmcnt(2)
	v_mfma_f32_16x16x32_bf16 v[28:31], v[148:151], v[242:245], v[28:31]
	v_mfma_f32_16x16x32_bf16 v[12:15], v[148:151], v[246:249], v[12:15]
	ds_read_b128 v[148:151], v147 offset:32768
	v_mfma_f32_16x16x32_bf16 v[24:27], v[152:155], v[242:245], v[24:27]
	v_mfma_f32_16x16x32_bf16 v[4:7], v[152:155], v[246:249], v[4:7]
	s_add_i32 m0, s54, 0x8000
	v_lshl_add_u64 v[254:255], v[138:139], 0, s[12:13]
	global_load_lds_dwordx4 v[254:255], off
	ds_read_b128 v[152:155], v147 offset:34816
	v_mfma_f32_16x16x32_bf16 v[20:23], v[164:167], v[242:245], v[20:23]
	v_mfma_f32_16x16x32_bf16 v[0:3], v[164:167], v[246:249], v[0:3]
	ds_read_b128 v[164:167], v147 offset:36864
	v_mfma_f32_16x16x32_bf16 v[16:19], v[168:171], v[242:245], v[16:19]
	v_mfma_f32_16x16x32_bf16 v[8:11], v[168:171], v[246:249], v[8:11]
	s_add_i32 m0, s54, 0xa000
	v_lshl_add_u64 v[254:255], v[140:141], 0, s[12:13]
	global_load_lds_dwordx4 v[254:255], off
	s_add_i32 s3, s3, 1
	s_cmpk_lg_i32 s12, 0x800
	ds_read_b128 v[168:171], v147 offset:38912
	ds_read_b128 v[242:245], v172 offset:4096
	ds_read_b128 v[246:249], v172 offset:6144
	s_waitcnt lgkmcnt(2)
	v_mfma_f32_16x16x32_bf16 v[60:63], v[148:151], v[156:159], v[60:63]
	v_mfma_f32_16x16x32_bf16 v[44:47], v[148:151], v[160:163], v[44:47]
	v_mfma_f32_16x16x32_bf16 v[56:59], v[152:155], v[156:159], v[56:59]
	v_mfma_f32_16x16x32_bf16 v[40:43], v[152:155], v[160:163], v[40:43]
	v_mfma_f32_16x16x32_bf16 v[52:55], v[164:167], v[156:159], v[52:55]
	v_mfma_f32_16x16x32_bf16 v[36:39], v[164:167], v[160:163], v[36:39]
	v_mfma_f32_16x16x32_bf16 v[48:51], v[168:171], v[156:159], v[48:51]
	v_mfma_f32_16x16x32_bf16 v[32:35], v[168:171], v[160:163], v[32:35]
	s_cbranch_scc0 .Lg3l_gemm7
	s_waitcnt vmcnt(6) lgkmcnt(0)
	s_branch .Lg3j_gemm7
.Lg3l_gemm7:
	s_waitcnt lgkmcnt(0)
.Lg3j_gemm7:
	v_mfma_f32_16x16x32_bf16 v[28:31], v[148:151], v[242:245], v[28:31]
	s_barrier
	v_mfma_f32_16x16x32_bf16 v[12:15], v[148:151], v[246:249], v[12:15]
	v_mfma_f32_16x16x32_bf16 v[24:27], v[152:155], v[242:245], v[24:27]
	v_mfma_f32_16x16x32_bf16 v[4:7], v[152:155], v[246:249], v[4:7]
	v_mfma_f32_16x16x32_bf16 v[20:23], v[164:167], v[242:245], v[20:23]
	v_mfma_f32_16x16x32_bf16 v[0:3], v[164:167], v[246:249], v[0:3]
	v_mfma_f32_16x16x32_bf16 v[16:19], v[168:171], v[242:245], v[16:19]
	v_mfma_f32_16x16x32_bf16 v[8:11], v[168:171], v[246:249], v[8:11]
	s_cbranch_scc0 .LBB0_736

.Lg3a_gemm6:
	s_mul_i32 m0, m0, 0xc000
	s_add_i32 s54, s54, m0
	s_mul_i32 s53, s53, 0xc000
	s_add_i32 s53, s53, 0
	v_add3_u32 v64, s53, v209, v210
	v_add_u32_e32 v234, v64, v212
	v_add3_u32 v238, s53, v211, v210
	v_add_u32_e32 v239, v238, v212
	ds_read_b128 v[214:217], v234 offset:32768
	ds_read_b128 v[218:221], v234 offset:34816
	ds_read_b128 v[230:233], v234 offset:36864
	ds_read_b128 v[234:237], v234 offset:38912
	ds_read_b128 v[222:225], v239
	ds_read_b128 v[226:229], v239 offset:2048
	ds_read_b128 v[242:245], v239 offset:4096
	ds_read_b128 v[246:249], v239 offset:6144
	s_add_u32 s12, s12, 0x80
	s_addc_u32 s13, s13, 0
	s_mov_b32 m0, s54
	v_lshl_add_u64 v[254:255], v[130:131], 0, s[12:13]
	global_load_lds_dwordx4 v[254:255], off
	s_add_i32 m0, s54, 0x2000
	v_lshl_add_u64 v[254:255], v[132:133], 0, s[12:13]
	global_load_lds_dwordx4 v[254:255], off
	s_waitcnt lgkmcnt(2)
	v_mfma_f32_16x16x32_bf16 v[60:63], v[214:217], v[222:225], v[60:63]
	v_add_u32_e32 v64, v64, v213
	v_add_u32_e32 v238, v238, v213
	v_mfma_f32_16x16x32_bf16 v[44:47], v[214:217], v[226:229], v[44:47]
	v_mfma_f32_16x16x32_bf16 v[56:59], v[218:221], v[222:225], v[56:59]
	v_mfma_f32_16x16x32_bf16 v[40:43], v[218:221], v[226:229], v[40:43]
	s_add_i32 m0, s54, 0x4000
	v_lshl_add_u64 v[254:255], v[134:135], 0, s[12:13]
	global_load_lds_dwordx4 v[254:255], off
	v_mfma_f32_16x16x32_bf16 v[52:55], v[230:233], v[222:225], v[52:55]
	v_mfma_f32_16x16x32_bf16 v[36:39], v[230:233], v[226:229], v[36:39]
	v_mfma_f32_16x16x32_bf16 v[48:51], v[234:237], v[222:225], v[48:51]
	v_mfma_f32_16x16x32_bf16 v[32:35], v[234:237], v[226:229], v[32:35]
	s_add_i32 m0, s54, 0x6000
	v_lshl_add_u64 v[254:255], v[136:137], 0, s[12:13]
	global_load_lds_dwordx4 v[254:255], off
	ds_read_b128 v[222:225], v238
	ds_read_b128 v[226:229], v238 offset:2048
	s_waitcnt lgkmcnt(2)
	v_mfma_f32_16x16x32_bf16 v[28:31], v[214:217], v[242:245], v[28:31]
	v_mfma_f32_16x16x32_bf16 v[12:15], v[214:217], v[246:249], v[12:15]
	ds_read_b128 v[214:217], v64 offset:32768
	v_mfma_f32_16x16x32_bf16 v[24:27], v[218:221], v[242:245], v[24:27]
	v_mfma_f32_16x16x32_bf16 v[8:11], v[218:221], v[246:249], v[8:11]
	s_add_i32 m0, s54, 0x8000
	v_lshl_add_u64 v[254:255], v[138:139], 0, s[12:13]
	global_load_lds_dwordx4 v[254:255], off
	ds_read_b128 v[218:221], v64 offset:34816
	v_mfma_f32_16x16x32_bf16 v[20:23], v[230:233], v[242:245], v[20:23]
	v_mfma_f32_16x16x32_bf16 v[4:7], v[230:233], v[246:249], v[4:7]
	ds_read_b128 v[230:233], v64 offset:36864
	v_mfma_f32_16x16x32_bf16 v[16:19], v[234:237], v[242:245], v[16:19]
	v_mfma_f32_16x16x32_bf16 v[0:3], v[234:237], v[246:249], v[0:3]
	s_add_i32 m0, s54, 0xa000
	v_lshl_add_u64 v[254:255], v[140:141], 0, s[12:13]
	global_load_lds_dwordx4 v[254:255], off
	s_add_i32 s3, s3, 1
	s_cmpk_lg_i32 s12, 0x400
	ds_read_b128 v[234:237], v64 offset:38912
	ds_read_b128 v[242:245], v238 offset:4096
	ds_read_b128 v[246:249], v238 offset:6144
	s_waitcnt lgkmcnt(2)
	v_mfma_f32_16x16x32_bf16 v[60:63], v[214:217], v[222:225], v[60:63]
	v_mfma_f32_16x16x32_bf16 v[44:47], v[214:217], v[226:229], v[44:47]
	v_mfma_f32_16x16x32_bf16 v[56:59], v[218:221], v[222:225], v[56:59]
	v_mfma_f32_16x16x32_bf16 v[40:43], v[218:221], v[226:229], v[40:43]
	v_mfma_f32_16x16x32_bf16 v[52:55], v[230:233], v[222:225], v[52:55]
	v_mfma_f32_16x16x32_bf16 v[36:39], v[230:233], v[226:229], v[36:39]
	v_mfma_f32_16x16x32_bf16 v[48:51], v[234:237], v[222:225], v[48:51]
	v_mfma_f32_16x16x32_bf16 v[32:35], v[234:237], v[226:229], v[32:35]
	s_cbranch_scc0 .Lg3l_gemm6
	s_waitcnt vmcnt(6) lgkmcnt(0)
	s_branch .Lg3j_gemm6
.Lg3l_gemm6:
	s_waitcnt lgkmcnt(0)
.Lg3j_gemm6:
	v_mfma_f32_16x16x32_bf16 v[28:31], v[214:217], v[242:245], v[28:31]
	s_barrier
	v_mfma_f32_16x16x32_bf16 v[12:15], v[214:217], v[246:249], v[12:15]
	v_mfma_f32_16x16x32_bf16 v[24:27], v[218:221], v[242:245], v[24:27]
	v_mfma_f32_16x16x32_bf16 v[8:11], v[218:221], v[246:249], v[8:11]
	v_mfma_f32_16x16x32_bf16 v[20:23], v[230:233], v[242:245], v[20:23]
	v_mfma_f32_16x16x32_bf16 v[4:7], v[230:233], v[246:249], v[4:7]
	v_mfma_f32_16x16x32_bf16 v[16:19], v[234:237], v[242:245], v[16:19]
	v_mfma_f32_16x16x32_bf16 v[0:3], v[234:237], v[246:249], v[0:3]
	s_cbranch_scc0 .LBB0_731

.LBB0_764:
	s_and_b32 s14, s23, 7
	s_mul_i32 s14, s14, 0x142000
	s_add_i32 s14, s0, s14
	s_lshl_b32 s31, s14, 1
	s_and_b32 s14, s26, 0xffffff00
	s_ashr_i32 s15, s14, 31
	s_lshl_b64 s[16:17], s[14:15], 11
	s_and_b32 s14, s29, 7
	v_mov_b32_e32 v32, v198
	s_or_b32 s30, s14, s69
	s_lshl_b32 s14, s29, 5
	s_and_b32 s14, s14, 0xffffff00
	v_ashrrev_i32_e32 v33, 6, v32
	v_bfe_u32 v0, v32, 3, 3
	s_mul_i32 s15, s30, 0x284000
	v_lshl_or_b32 v0, v33, 3, v0
	s_add_u32 s18, s1, s15
	v_lshrrev_b32_e32 v35, 1, v0
	s_addc_u32 s19, s20, 0
	v_xor_b32_e32 v6, v35, v32
	s_ashr_i32 s15, s14, 31
	v_mov_b64_e32 v[2:3], s[18:19]
	v_lshlrev_b32_e32 v6, 4, v6
	v_lshl_add_u32 v146, v33, 10, 0
	s_lshl_b64 s[34:35], s[14:15], 11
	v_mad_i64_i32 v[4:5], s[18:19], v0, s28, v[2:3]
	v_and_b32_e32 v128, 0x70, v6
	v_readfirstlane_b32 s15, v146
	v_lshl_add_u64 v[4:5], v[4:5], 0, v[128:129]
	s_mov_b32 m0, s15
	v_add_u32_e32 v6, 64, v0
	global_load_lds_dwordx4 v[4:5], off
	v_add_u32_e32 v4, 0x2000, v146
	v_mad_i64_i32 v[8:9], s[18:19], v6, s28, v[2:3]
	v_add_u32_e32 v10, 0x80, v0
	v_readfirstlane_b32 s15, v4
	v_add_u32_e32 v4, 0x4000, v146
	v_lshl_add_u64 v[8:9], v[8:9], 0, v[128:129]
	v_mad_i64_i32 v[12:13], s[18:19], v10, s28, v[2:3]
	v_add_u32_e32 v14, 0xc0, v0
	s_mov_b32 m0, s15
	v_readfirstlane_b32 s15, v4
	v_add_u32_e32 v4, 0x6000, v146
	v_lshl_add_u64 v[12:13], v[12:13], 0, v[128:129]
	v_mad_i64_i32 v[2:3], s[18:19], v14, s28, v[2:3]
	global_load_lds_dwordx4 v[8:9], off
	s_mov_b32 m0, s15
	v_readfirstlane_b32 s15, v4
	s_add_u32 s34, s21, s34
	v_ashrrev_i32_e32 v1, 31, v0
	v_lshl_add_u64 v[2:3], v[2:3], 0, v[128:129]
	global_load_lds_dwordx4 v[12:13], off
	s_mov_b32 m0, s15
	s_addc_u32 s35, s22, s35
	v_ashrrev_i32_e32 v7, 31, v6
	v_lshlrev_b64 v[16:17], 11, v[0:1]
	global_load_lds_dwordx4 v[2:3], off
	v_add_u32_e32 v2, 0x8000, v146
	v_ashrrev_i32_e32 v11, 31, v10
	v_lshl_add_u64 v[18:19], s[34:35], 0, v[16:17]
	v_lshlrev_b64 v[20:21], 11, v[6:7]
	v_readfirstlane_b32 s15, v2
	v_add_u32_e32 v2, 0xa000, v146
	v_ashrrev_i32_e32 v15, 31, v14
	v_lshl_add_u64 v[18:19], v[18:19], 0, v[128:129]
	v_lshl_add_u64 v[22:23], s[34:35], 0, v[20:21]
	v_lshlrev_b64 v[24:25], 11, v[10:11]
	s_mov_b32 m0, s15
	v_readfirstlane_b32 s15, v2
	v_add_u32_e32 v2, 0xc000, v146
	v_lshl_add_u64 v[22:23], v[22:23], 0, v[128:129]
	v_lshl_add_u64 v[26:27], s[34:35], 0, v[24:25]
	v_lshlrev_b64 v[28:29], 11, v[14:15]
	global_load_lds_dwordx4 v[18:19], off
	s_mov_b32 m0, s15
	v_readfirstlane_b32 s15, v2
	v_add_u32_e32 v2, 0xe000, v146
	v_lshl_add_u64 v[26:27], v[26:27], 0, v[128:129]
	v_lshl_add_u64 v[30:31], s[34:35], 0, v[28:29]
	global_load_lds_dwordx4 v[22:23], off
	s_mov_b32 m0, s15
	v_readfirstlane_b32 s15, v2
	v_lshl_add_u64 v[30:31], v[30:31], 0, v[128:129]
	global_load_lds_dwordx4 v[26:27], off
	s_mov_b32 m0, s15
	v_lshrrev_b32_e32 v2, 30, v33
	global_load_lds_dwordx4 v[30:31], off
	v_add_u32_e32 v2, v33, v2
	v_bfe_u32 v1, v32, 4, 2
	v_bfe_u32 v7, v32, 1, 3
	v_ashrrev_i32_e32 v2, 2, v2
	v_mul_i32_i24_e32 v3, 4, v2
	v_lshlrev_b32_e32 v149, 14, v2
	v_xor_b32_e32 v2, v1, v7
	v_bitop3_b32 v1, v1, v7, 4 bitop3:0x36
	v_lshlrev_b32_e32 v151, 4, v1
	v_bitop3_b32 v1, v35, 7, v32 bitop3:0x48
	v_lshlrev_b32_e32 v128, 4, v1
	v_mad_i64_i32 v[0:1], s[18:19], v0, s28, v[128:129]
	s_add_u32 s18, s24, s31
	s_addc_u32 s19, s25, 0
	v_lshl_add_u64 v[130:131], s[18:19], 0, v[0:1]
	v_mad_i64_i32 v[0:1], s[34:35], v6, s28, v[128:129]
	v_lshl_add_u64 v[132:133], s[18:19], 0, v[0:1]
	v_mad_i64_i32 v[0:1], s[34:35], v10, s28, v[128:129]
	v_lshl_add_u64 v[134:135], s[18:19], 0, v[0:1]
	v_mad_i64_i32 v[0:1], s[34:35], v14, s28, v[128:129]
	v_lshl_add_u64 v[136:137], s[18:19], 0, v[0:1]
	v_lshl_add_u64 v[0:1], s[16:17], 0, v[16:17]
	v_or_b32_e32 v0, v0, v128
	v_lshl_add_u64 v[138:139], s[10:11], 0, v[0:1]
	v_lshl_add_u64 v[0:1], s[16:17], 0, v[20:21]
	v_or_b32_e32 v0, v0, v128
	v_lshl_add_u64 v[140:141], s[10:11], 0, v[0:1]
	v_lshl_add_u64 v[0:1], s[16:17], 0, v[24:25]
	v_or_b32_e32 v0, v0, v128
	v_lshl_add_u64 v[142:143], s[10:11], 0, v[0:1]
	v_lshl_add_u64 v[0:1], s[16:17], 0, v[28:29]
	v_and_b32_e32 v34, 15, v32
	v_sub_u32_e32 v3, v33, v3
	v_or_b32_e32 v0, v0, v128
	v_lshlrev_b32_e32 v147, 13, v3
	v_lshlrev_b32_e32 v148, 7, v34
	v_lshlrev_b32_e32 v150, 4, v2
	v_lshl_add_u64 v[144:145], s[10:11], 0, v[0:1]
	s_mov_b32 s15, 0
	s_mov_b64 s[16:17], 0
	v_mov_b32_e32 v24, 0
	v_mov_b32_e32 v25, v129
	v_mov_b32_e32 v26, v129
	v_mov_b32_e32 v27, v129
	v_mov_b32_e32 v0, 0
	v_mov_b32_e32 v1, v129
	v_mov_b32_e32 v2, v129
	v_mov_b32_e32 v3, v129
	v_mov_b32_e32 v4, 0
	v_mov_b32_e32 v5, v129
	v_mov_b32_e32 v6, v129
	v_mov_b32_e32 v7, v129
	v_mov_b32_e32 v8, 0
	v_mov_b32_e32 v9, v129
	v_mov_b32_e32 v10, v129
	v_mov_b32_e32 v11, v129
	v_mov_b32_e32 v12, 0
	v_mov_b32_e32 v13, v129
	v_mov_b32_e32 v14, v129
	v_mov_b32_e32 v15, v129
	v_mov_b32_e32 v16, 0
	v_mov_b32_e32 v17, v129
	v_mov_b32_e32 v18, v129
	v_mov_b32_e32 v19, v129
	v_mov_b32_e32 v20, 0
	v_mov_b32_e32 v21, v129
	v_mov_b32_e32 v22, v129
	v_mov_b32_e32 v23, v129
	v_mov_b32_e32 v28, 0
	v_mov_b32_e32 v29, v129
	v_mov_b32_e32 v30, v129
	v_mov_b32_e32 v31, v129
	v_mov_b32_e32 v32, 0
	v_mov_b32_e32 v33, v129
	v_mov_b32_e32 v34, v129
	v_mov_b32_e32 v35, v129
	v_mov_b32_e32 v36, 0
	v_mov_b32_e32 v37, v129
	v_mov_b32_e32 v38, v129
	v_mov_b32_e32 v39, v129
	v_mov_b32_e32 v40, 0
	v_mov_b32_e32 v41, v129
	v_mov_b32_e32 v42, v129
	v_mov_b32_e32 v43, v129
	v_mov_b32_e32 v44, 0
	v_mov_b32_e32 v45, v129
	v_mov_b32_e32 v46, v129
	v_mov_b32_e32 v47, v129
	v_mov_b32_e32 v48, 0
	v_mov_b32_e32 v49, v129
	v_mov_b32_e32 v50, v129
	v_mov_b32_e32 v51, v129
	v_mov_b32_e32 v52, 0
	v_mov_b32_e32 v53, v129
	v_mov_b32_e32 v54, v129
	v_mov_b32_e32 v55, v129
	v_mov_b32_e32 v56, 0
	v_mov_b32_e32 v57, v129
	v_mov_b32_e32 v58, v129
	v_mov_b32_e32 v59, v129
	v_mov_b32_e32 v60, 0
	v_mov_b32_e32 v61, v129
	v_mov_b32_e32 v62, v129
	v_mov_b32_e32 v63, v129
	v_mov_b32_e32 v64, 0
	v_mov_b32_e32 v65, v129
	v_mov_b32_e32 v66, v129
	v_mov_b32_e32 v67, v129
	v_mov_b32_e32 v68, 0
	v_mov_b32_e32 v69, v129
	v_mov_b32_e32 v70, v129
	v_mov_b32_e32 v71, v129
	v_mov_b32_e32 v72, 0
	v_mov_b32_e32 v73, v129
	v_mov_b32_e32 v74, v129
	v_mov_b32_e32 v75, v129
	v_mov_b32_e32 v76, 0
	v_mov_b32_e32 v77, v129
	v_mov_b32_e32 v78, v129
	v_mov_b32_e32 v79, v129
	v_mov_b32_e32 v80, 0
	v_mov_b32_e32 v81, v129
	v_mov_b32_e32 v82, v129
	v_mov_b32_e32 v83, v129
	v_mov_b32_e32 v84, 0
	v_mov_b32_e32 v85, v129
	v_mov_b32_e32 v86, v129
	v_mov_b32_e32 v87, v129
	v_mov_b32_e32 v88, 0
	v_mov_b32_e32 v89, v129
	v_mov_b32_e32 v90, v129
	v_mov_b32_e32 v91, v129
	v_mov_b32_e32 v92, 0
	v_mov_b32_e32 v93, v129
	v_mov_b32_e32 v94, v129
	v_mov_b32_e32 v95, v129
	v_mov_b32_e32 v96, 0
	v_mov_b32_e32 v97, v129
	v_mov_b32_e32 v98, v129
	v_mov_b32_e32 v99, v129
	v_mov_b32_e32 v100, 0
	v_mov_b32_e32 v101, v129
	v_mov_b32_e32 v102, v129
	v_mov_b32_e32 v103, v129
	v_mov_b32_e32 v104, 0
	v_mov_b32_e32 v105, v129
	v_mov_b32_e32 v106, v129
	v_mov_b32_e32 v107, v129
	v_mov_b32_e32 v108, 0
	v_mov_b32_e32 v109, v129
	v_mov_b32_e32 v110, v129
	v_mov_b32_e32 v111, v129
	v_mov_b32_e32 v112, 0
	v_mov_b32_e32 v113, v129
	v_mov_b32_e32 v114, v129
	v_mov_b32_e32 v115, v129
	v_mov_b32_e32 v116, 0
	v_mov_b32_e32 v117, v129
	v_mov_b32_e32 v118, v129
	v_mov_b32_e32 v119, v129
	v_mov_b32_e32 v120, 0
	v_mov_b32_e32 v121, v129
	v_mov_b32_e32 v122, v129
	v_mov_b32_e32 v123, v129
	v_mov_b32_e32 v124, 0
	v_mov_b32_e32 v125, v129
	v_mov_b32_e32 v126, v129
	v_mov_b32_e32 v127, v129
	s_waitcnt vmcnt(0) lgkmcnt(0)
	s_barrier
	s_branch .LBB0_766

.LBB0_1150:
	v_cmp_lt_i32_e32 vcc, 7, v0
	s_and_saveexec_b64 s[2:3], vcc
	s_xor_b64 s[50:51], exec, s[2:3]
	s_cbranch_execz .LBB0_1346
	v_cmp_lt_u32_e32 vcc, 15, v0
	s_and_saveexec_b64 s[2:3], vcc
	s_xor_b64 s[64:65], exec, s[2:3]
	s_cbranch_execz .LBB0_1337
	v_cmp_lt_u32_e32 vcc, 23, v0
	s_and_saveexec_b64 s[2:3], vcc
	s_xor_b64 s[66:67], exec, s[2:3]
	s_cbranch_execz .LBB0_1332
	v_cmp_lt_u32_e32 vcc, 55, v0
	s_and_saveexec_b64 s[2:3], vcc
	s_xor_b64 s[4:5], exec, s[2:3]
	s_cbranch_execz .LBB0_1225
	v_readlane_b32 s2, v240, 24
	v_mov_b32_e32 v36, v198
	v_and_b32_e32 v148, 3, v0
	v_add_u32_e32 v1, s2, v0
	v_lshrrev_b32_e32 v149, 2, v1
	s_mov_b32 s2, 0x142000
	v_mul_lo_u32 v168, v149, s2
	v_ashrrev_i32_e32 v37, 6, v36
	v_bfe_u32 v6, v36, 3, 3
	v_lshlrev_b64 v[0:1], 1, v[168:169]
	v_lshl_or_b32 v6, v37, 3, v6
	v_lshl_add_u64 v[2:3], s[62:63], 0, v[0:1]
	s_mov_b64 s[2:3], 0x38e1600
	v_lshrrev_b32_e32 v39, 1, v6
	v_lshl_add_u64 v[2:3], v[2:3], 0, s[2:3]
	v_xor_b32_e32 v10, v39, v36
	v_add_u32_e32 v12, 64, v6
	v_add_u32_e32 v16, 0x80, v6
	v_add_u32_e32 v20, 0xc0, v6
	v_mad_i64_i32 v[8:9], s[2:3], v6, s59, v[2:3]
	v_lshlrev_b32_e32 v10, 4, v10
	v_mad_i64_i32 v[14:15], s[2:3], v12, s59, v[2:3]
	v_mad_i64_i32 v[18:19], s[2:3], v16, s59, v[2:3]
	v_mad_i64_i32 v[2:3], s[2:3], v20, s59, v[2:3]
	v_lshl_add_u32 v150, v37, 10, 0
	v_and_b32_e32 v10, 0x70, v10
	v_mov_b32_e32 v11, v169
	v_readfirstlane_b32 s2, v150
	v_lshl_add_u64 v[8:9], v[8:9], 0, v[10:11]
	s_mov_b32 m0, s2
	v_lshl_add_u64 v[14:15], v[14:15], 0, v[10:11]
	global_load_lds_dwordx4 v[8:9], off
	v_add_u32_e32 v8, 0x2000, v150
	v_lshl_add_u64 v[18:19], v[18:19], 0, v[10:11]
	v_readfirstlane_b32 s2, v8
	v_add_u32_e32 v8, 0x4000, v150
	s_mov_b32 m0, s2
	v_readfirstlane_b32 s2, v8
	v_add_u32_e32 v8, 0x6000, v150
	global_load_lds_dwordx4 v[14:15], off
	s_mov_b32 m0, s2
	v_readfirstlane_b32 s2, v8
	v_lshlrev_b32_e32 v168, 17, v148
	v_ashrrev_i32_e32 v7, 31, v6
	v_lshl_add_u64 v[2:3], v[2:3], 0, v[10:11]
	global_load_lds_dwordx4 v[18:19], off
	s_mov_b32 m0, s2
	v_lshl_add_u64 v[4:5], s[12:13], 0, v[168:169]
	v_ashrrev_i32_e32 v13, 31, v12
	v_lshlrev_b64 v[22:23], 9, v[6:7]
	global_load_lds_dwordx4 v[2:3], off
	v_add_u32_e32 v2, 0x8000, v150
	v_ashrrev_i32_e32 v17, 31, v16
	v_lshl_add_u64 v[24:25], v[4:5], 0, v[22:23]
	v_lshlrev_b64 v[26:27], 9, v[12:13]
	v_readfirstlane_b32 s2, v2
	v_add_u32_e32 v2, 0xa000, v150
	v_ashrrev_i32_e32 v21, 31, v20
	v_lshl_add_u64 v[24:25], v[24:25], 0, v[10:11]
	v_lshl_add_u64 v[28:29], v[4:5], 0, v[26:27]
	v_lshlrev_b64 v[30:31], 9, v[16:17]
	s_mov_b32 m0, s2
	v_readfirstlane_b32 s2, v2
	v_add_u32_e32 v2, 0xc000, v150
	v_lshl_add_u64 v[28:29], v[28:29], 0, v[10:11]
	v_lshl_add_u64 v[32:33], v[4:5], 0, v[30:31]
	v_lshlrev_b64 v[34:35], 9, v[20:21]
	global_load_lds_dwordx4 v[24:25], off
	s_mov_b32 m0, s2
	v_readfirstlane_b32 s2, v2
	v_add_u32_e32 v2, 0xe000, v150
	v_lshl_add_u64 v[32:33], v[32:33], 0, v[10:11]
	v_lshl_add_u64 v[4:5], v[4:5], 0, v[34:35]
	global_load_lds_dwordx4 v[28:29], off
	s_mov_b32 m0, s2
	v_readfirstlane_b32 s2, v2
	v_lshl_add_u64 v[4:5], v[4:5], 0, v[10:11]
	global_load_lds_dwordx4 v[32:33], off
	s_mov_b32 m0, s2
	v_lshrrev_b32_e32 v2, 30, v37
	global_load_lds_dwordx4 v[4:5], off
	v_add_u32_e32 v2, v37, v2
	v_bfe_u32 v7, v36, 4, 2
	v_bfe_u32 v10, v36, 1, 3
	v_ashrrev_i32_e32 v2, 2, v2
	v_mul_i32_i24_e32 v3, 4, v2
	v_lshlrev_b32_e32 v153, 14, v2
	v_xor_b32_e32 v2, v7, v10
	v_lshlrev_b32_e32 v154, 4, v2
	v_bitop3_b32 v2, v7, v10, 4 bitop3:0x36
	v_sub_u32_e32 v3, v37, v3
	v_lshlrev_b32_e32 v155, 4, v2
	v_bitop3_b32 v2, v39, 7, v36 bitop3:0x48
	v_lshlrev_b32_e32 v151, 13, v3
	v_lshlrev_b32_e32 v2, 4, v2
	v_mov_b32_e32 v3, v169
	v_mad_i64_i32 v[4:5], s[2:3], v6, s59, v[2:3]
	v_lshl_add_u64 v[4:5], v[4:5], 0, v[0:1]
	v_lshl_add_u64 v[132:133], s[38:39], 0, v[4:5]
	v_mad_i64_i32 v[4:5], s[2:3], v12, s59, v[2:3]
	v_lshl_add_u64 v[4:5], v[4:5], 0, v[0:1]
	v_lshl_add_u64 v[134:135], s[38:39], 0, v[4:5]
	v_mad_i64_i32 v[4:5], s[2:3], v16, s59, v[2:3]
	v_lshl_add_u64 v[4:5], v[4:5], 0, v[0:1]
	v_lshl_add_u64 v[136:137], s[38:39], 0, v[4:5]
	v_mad_i64_i32 v[4:5], s[2:3], v20, s59, v[2:3]
	v_lshl_add_u64 v[0:1], v[4:5], 0, v[0:1]
	v_lshl_add_u64 v[138:139], s[38:39], 0, v[0:1]
	v_lshl_add_u64 v[0:1], v[168:169], 0, v[22:23]
	v_or_b32_e32 v0, v0, v2
	v_lshl_add_u64 v[140:141], s[40:41], 0, v[0:1]
	v_lshl_add_u64 v[0:1], v[168:169], 0, v[26:27]
	v_or_b32_e32 v0, v0, v2
	v_lshl_add_u64 v[142:143], s[40:41], 0, v[0:1]
	v_lshl_add_u64 v[0:1], v[168:169], 0, v[30:31]
	v_or_b32_e32 v0, v0, v2
	v_lshl_add_u64 v[144:145], s[40:41], 0, v[0:1]
	v_lshl_add_u64 v[0:1], v[168:169], 0, v[34:35]
	v_and_b32_e32 v38, 15, v36
	v_or_b32_e32 v0, v0, v2
	v_mov_b32_e32 v4, 0
	v_lshlrev_b32_e32 v152, 7, v38
	v_lshl_add_u64 v[146:147], s[40:41], 0, v[0:1]
	s_mov_b32 s74, 0
	s_mov_b64 s[2:3], 0
	v_mov_b32_e32 v5, v4
	v_mov_b32_e32 v6, v4
	v_mov_b32_e32 v7, v4
	v_mov_b32_e32 v0, v4
	v_mov_b32_e32 v1, v4
	v_mov_b32_e32 v2, v4
	v_mov_b32_e32 v3, v4
	v_mov_b32_e32 v8, v4
	v_mov_b32_e32 v9, v4
	v_mov_b32_e32 v10, v4
	v_mov_b32_e32 v11, v4
	v_mov_b32_e32 v12, v4
	v_mov_b32_e32 v13, v4
	v_mov_b32_e32 v14, v4
	v_mov_b32_e32 v15, v4
	v_mov_b32_e32 v16, v4
	v_mov_b32_e32 v17, v4
	v_mov_b32_e32 v18, v4
	v_mov_b32_e32 v19, v4
	v_mov_b32_e32 v20, v4
	v_mov_b32_e32 v21, v4
	v_mov_b32_e32 v22, v4
	v_mov_b32_e32 v23, v4
	v_mov_b32_e32 v24, v4
	v_mov_b32_e32 v25, v4
	v_mov_b32_e32 v26, v4
	v_mov_b32_e32 v27, v4
	v_mov_b32_e32 v28, v4
	v_mov_b32_e32 v29, v4
	v_mov_b32_e32 v30, v4
	v_mov_b32_e32 v31, v4
	v_mov_b32_e32 v32, v4
	v_mov_b32_e32 v33, v4
	v_mov_b32_e32 v34, v4
	v_mov_b32_e32 v35, v4
	v_mov_b32_e32 v36, v4
	v_mov_b32_e32 v37, v4
	v_mov_b32_e32 v38, v4
	v_mov_b32_e32 v39, v4
	v_mov_b32_e32 v40, v4
	v_mov_b32_e32 v41, v4
	v_mov_b32_e32 v42, v4
	v_mov_b32_e32 v43, v4
	v_mov_b32_e32 v44, v4
	v_mov_b32_e32 v45, v4
	v_mov_b32_e32 v46, v4
	v_mov_b32_e32 v47, v4
	v_mov_b32_e32 v48, v4
	v_mov_b32_e32 v49, v4
	v_mov_b32_e32 v50, v4
	v_mov_b32_e32 v51, v4
	v_mov_b32_e32 v52, v4
	v_mov_b32_e32 v53, v4
	v_mov_b32_e32 v54, v4
	v_mov_b32_e32 v55, v4
	v_mov_b32_e32 v56, v4
	v_mov_b32_e32 v57, v4
	v_mov_b32_e32 v58, v4
	v_mov_b32_e32 v59, v4
	v_mov_b32_e32 v60, v4
	v_mov_b32_e32 v61, v4
	v_mov_b32_e32 v62, v4
	v_mov_b32_e32 v63, v4
	v_mov_b32_e32 v64, v4
	v_mov_b32_e32 v65, v4
	v_mov_b32_e32 v66, v4
	v_mov_b32_e32 v67, v4
	v_mov_b32_e32 v68, v4
	v_mov_b32_e32 v69, v4
	v_mov_b32_e32 v70, v4
	v_mov_b32_e32 v71, v4
	v_mov_b32_e32 v72, v4
	v_mov_b32_e32 v73, v4
	v_mov_b32_e32 v74, v4
	v_mov_b32_e32 v75, v4
	v_mov_b32_e32 v76, v4
	v_mov_b32_e32 v77, v4
	v_mov_b32_e32 v78, v4
	v_mov_b32_e32 v79, v4
	v_mov_b32_e32 v80, v4
	v_mov_b32_e32 v81, v4
	v_mov_b32_e32 v82, v4
	v_mov_b32_e32 v83, v4
	v_mov_b32_e32 v84, v4
	v_mov_b32_e32 v85, v4
	v_mov_b32_e32 v86, v4
	v_mov_b32_e32 v87, v4
	v_mov_b32_e32 v88, v4
	v_mov_b32_e32 v89, v4
	v_mov_b32_e32 v90, v4
	v_mov_b32_e32 v91, v4
	v_mov_b32_e32 v92, v4
	v_mov_b32_e32 v93, v4
	v_mov_b32_e32 v94, v4
	v_mov_b32_e32 v95, v4
	v_mov_b32_e32 v96, v4
	v_mov_b32_e32 v97, v4
	v_mov_b32_e32 v98, v4
	v_mov_b32_e32 v99, v4
	v_mov_b32_e32 v100, v4
	v_mov_b32_e32 v101, v4
	v_mov_b32_e32 v102, v4
	v_mov_b32_e32 v103, v4
	v_mov_b32_e32 v104, v4
	v_mov_b32_e32 v105, v4
	v_mov_b32_e32 v106, v4
	v_mov_b32_e32 v107, v4
	v_mov_b32_e32 v108, v4
	v_mov_b32_e32 v109, v4
	v_mov_b32_e32 v110, v4
	v_mov_b32_e32 v111, v4
	v_mov_b32_e32 v112, v4
	v_mov_b32_e32 v113, v4
	v_mov_b32_e32 v114, v4
	v_mov_b32_e32 v115, v4
	v_mov_b32_e32 v116, v4
	v_mov_b32_e32 v117, v4
	v_mov_b32_e32 v118, v4
	v_mov_b32_e32 v119, v4
	v_mov_b32_e32 v120, v4
	v_mov_b32_e32 v121, v4
	v_mov_b32_e32 v122, v4
	v_mov_b32_e32 v123, v4
	v_mov_b32_e32 v124, v4
	v_mov_b32_e32 v125, v4
	v_mov_b32_e32 v126, v4
	v_mov_b32_e32 v127, v4
	s_waitcnt vmcnt(0) lgkmcnt(0)
	s_barrier
	s_branch .LBB0_1156

.Lg3a_gemm2:
	s_mul_i32 m0, m0, 0xc000
	s_add_i32 s46, s46, m0
	s_mul_i32 s45, s45, 0xc000
	s_add_i32 s45, s45, 0
	v_add3_u32 v147, s45, v142, v143
	v_add_u32_e32 v168, v147, v145
	v_add3_u32 v172, s45, v144, v143
	v_add_u32_e32 v173, v172, v145
	ds_read_b128 v[148:151], v168 offset:32768
	ds_read_b128 v[152:155], v168 offset:34816
	ds_read_b128 v[164:167], v168 offset:36864
	ds_read_b128 v[168:171], v168 offset:38912
	ds_read_b128 v[156:159], v173
	ds_read_b128 v[160:163], v173 offset:2048
	ds_read_b128 v[242:245], v173 offset:4096
	ds_read_b128 v[246:249], v173 offset:6144
	s_add_u32 s12, s12, 0x80
	s_addc_u32 s13, s13, 0
	s_mov_b32 m0, s46
	v_lshl_add_u64 v[254:255], v[130:131], 0, s[12:13]
	global_load_lds_dwordx4 v[254:255], off
	s_add_i32 m0, s46, 0x2000
	v_lshl_add_u64 v[254:255], v[132:133], 0, s[12:13]
	global_load_lds_dwordx4 v[254:255], off
	s_waitcnt lgkmcnt(2)
	v_mfma_f32_16x16x32_bf16 v[60:63], v[148:151], v[156:159], v[60:63]
	v_add_u32_e32 v147, v147, v146
	v_add_u32_e32 v172, v172, v146
	v_mfma_f32_16x16x32_bf16 v[44:47], v[148:151], v[160:163], v[44:47]
	v_mfma_f32_16x16x32_bf16 v[56:59], v[152:155], v[156:159], v[56:59]
	v_mfma_f32_16x16x32_bf16 v[40:43], v[152:155], v[160:163], v[40:43]
	s_add_i32 m0, s46, 0x4000
	v_lshl_add_u64 v[254:255], v[134:135], 0, s[12:13]
	global_load_lds_dwordx4 v[254:255], off
	v_mfma_f32_16x16x32_bf16 v[52:55], v[164:167], v[156:159], v[52:55]
	v_mfma_f32_16x16x32_bf16 v[36:39], v[164:167], v[160:163], v[36:39]
	v_mfma_f32_16x16x32_bf16 v[48:51], v[168:171], v[156:159], v[48:51]
	v_mfma_f32_16x16x32_bf16 v[32:35], v[168:171], v[160:163], v[32:35]
	s_add_i32 m0, s46, 0x6000
	v_lshl_add_u64 v[254:255], v[136:137], 0, s[12:13]
	global_load_lds_dwordx4 v[254:255], off
	ds_read_b128 v[156:159], v172
	ds_read_b128 v[160:163], v172 offset:2048
	s_waitcnt lgkmcnt(2)
	v_mfma_f32_16x16x32_bf16 v[28:31], v[148:151], v[242:245], v[28:31]
	v_mfma_f32_16x16x32_bf16 v[12:15], v[148:151], v[246:249], v[12:15]
	ds_read_b128 v[148:151], v147 offset:32768
	v_mfma_f32_16x16x32_bf16 v[24:27], v[152:155], v[242:245], v[24:27]
	v_mfma_f32_16x16x32_bf16 v[4:7], v[152:155], v[246:249], v[4:7]
	s_add_i32 m0, s46, 0x8000
	v_lshl_add_u64 v[254:255], v[138:139], 0, s[12:13]
	global_load_lds_dwordx4 v[254:255], off
	ds_read_b128 v[152:155], v147 offset:34816
	v_mfma_f32_16x16x32_bf16 v[20:23], v[164:167], v[242:245], v[20:23]
	v_mfma_f32_16x16x32_bf16 v[0:3], v[164:167], v[246:249], v[0:3]
	ds_read_b128 v[164:167], v147 offset:36864
	v_mfma_f32_16x16x32_bf16 v[16:19], v[168:171], v[242:245], v[16:19]
	v_mfma_f32_16x16x32_bf16 v[8:11], v[168:171], v[246:249], v[8:11]
	s_add_i32 m0, s46, 0xa000
	v_lshl_add_u64 v[254:255], v[140:141], 0, s[12:13]
	global_load_lds_dwordx4 v[254:255], off
	s_add_i32 s3, s3, 1
	s_cmpk_lg_i32 s12, 0x800
	ds_read_b128 v[168:171], v147 offset:38912
	ds_read_b128 v[242:245], v172 offset:4096
	ds_read_b128 v[246:249], v172 offset:6144
	s_waitcnt lgkmcnt(2)
	v_mfma_f32_16x16x32_bf16 v[60:63], v[148:151], v[156:159], v[60:63]
	v_mfma_f32_16x16x32_bf16 v[44:47], v[148:151], v[160:163], v[44:47]
	v_mfma_f32_16x16x32_bf16 v[56:59], v[152:155], v[156:159], v[56:59]
	v_mfma_f32_16x16x32_bf16 v[40:43], v[152:155], v[160:163], v[40:43]
	v_mfma_f32_16x16x32_bf16 v[52:55], v[164:167], v[156:159], v[52:55]
	v_mfma_f32_16x16x32_bf16 v[36:39], v[164:167], v[160:163], v[36:39]
	v_mfma_f32_16x16x32_bf16 v[48:51], v[168:171], v[156:159], v[48:51]
	v_mfma_f32_16x16x32_bf16 v[32:35], v[168:171], v[160:163], v[32:35]
	s_cbranch_scc0 .Lg3l_gemm2
	s_waitcnt vmcnt(6) lgkmcnt(0)
	s_branch .Lg3j_gemm2
.Lg3l_gemm2:
	s_waitcnt lgkmcnt(0)
.Lg3j_gemm2:
	v_mfma_f32_16x16x32_bf16 v[28:31], v[148:151], v[242:245], v[28:31]
	s_barrier
	v_mfma_f32_16x16x32_bf16 v[12:15], v[148:151], v[246:249], v[12:15]
	v_mfma_f32_16x16x32_bf16 v[24:27], v[152:155], v[242:245], v[24:27]
	v_mfma_f32_16x16x32_bf16 v[4:7], v[152:155], v[246:249], v[4:7]
	v_mfma_f32_16x16x32_bf16 v[20:23], v[164:167], v[242:245], v[20:23]
	v_mfma_f32_16x16x32_bf16 v[0:3], v[164:167], v[246:249], v[0:3]
	v_mfma_f32_16x16x32_bf16 v[16:19], v[168:171], v[242:245], v[16:19]
	v_mfma_f32_16x16x32_bf16 v[8:11], v[168:171], v[246:249], v[8:11]
	s_cbranch_scc0 .LBB0_1502

.Lg3a_gemm1:
	s_mul_i32 m0, m0, 0xc000
	s_add_i32 s46, s46, m0
	s_mul_i32 s45, s45, 0xc000
	s_add_i32 s45, s45, 0
	v_add3_u32 v64, s45, v209, v210
	v_add_u32_e32 v234, v64, v212
	v_add3_u32 v238, s45, v211, v210
	v_add_u32_e32 v239, v238, v212
	ds_read_b128 v[214:217], v234 offset:32768
	ds_read_b128 v[218:221], v234 offset:34816
	ds_read_b128 v[230:233], v234 offset:36864
	ds_read_b128 v[234:237], v234 offset:38912
	ds_read_b128 v[222:225], v239
	ds_read_b128 v[226:229], v239 offset:2048
	ds_read_b128 v[242:245], v239 offset:4096
	ds_read_b128 v[246:249], v239 offset:6144
	s_add_u32 s12, s12, 0x80
	s_addc_u32 s13, s13, 0
	s_mov_b32 m0, s46
	v_lshl_add_u64 v[254:255], v[130:131], 0, s[12:13]
	global_load_lds_dwordx4 v[254:255], off
	s_add_i32 m0, s46, 0x2000
	v_lshl_add_u64 v[254:255], v[132:133], 0, s[12:13]
	global_load_lds_dwordx4 v[254:255], off
	s_waitcnt lgkmcnt(2)
	v_mfma_f32_16x16x32_bf16 v[60:63], v[214:217], v[222:225], v[60:63]
	v_add_u32_e32 v64, v64, v213
	v_add_u32_e32 v238, v238, v213
	v_mfma_f32_16x16x32_bf16 v[44:47], v[214:217], v[226:229], v[44:47]
	v_mfma_f32_16x16x32_bf16 v[56:59], v[218:221], v[222:225], v[56:59]
	v_mfma_f32_16x16x32_bf16 v[40:43], v[218:221], v[226:229], v[40:43]
	s_add_i32 m0, s46, 0x4000
	v_lshl_add_u64 v[254:255], v[134:135], 0, s[12:13]
	global_load_lds_dwordx4 v[254:255], off
	v_mfma_f32_16x16x32_bf16 v[52:55], v[230:233], v[222:225], v[52:55]
	v_mfma_f32_16x16x32_bf16 v[36:39], v[230:233], v[226:229], v[36:39]
	v_mfma_f32_16x16x32_bf16 v[48:51], v[234:237], v[222:225], v[48:51]
	v_mfma_f32_16x16x32_bf16 v[32:35], v[234:237], v[226:229], v[32:35]
	s_add_i32 m0, s46, 0x6000
	v_lshl_add_u64 v[254:255], v[136:137], 0, s[12:13]
	global_load_lds_dwordx4 v[254:255], off
	ds_read_b128 v[222:225], v238
	ds_read_b128 v[226:229], v238 offset:2048
	s_waitcnt lgkmcnt(2)
	v_mfma_f32_16x16x32_bf16 v[28:31], v[214:217], v[242:245], v[28:31]
	v_mfma_f32_16x16x32_bf16 v[12:15], v[214:217], v[246:249], v[12:15]
	ds_read_b128 v[214:217], v64 offset:32768
	v_mfma_f32_16x16x32_bf16 v[24:27], v[218:221], v[242:245], v[24:27]
	v_mfma_f32_16x16x32_bf16 v[8:11], v[218:221], v[246:249], v[8:11]
	s_add_i32 m0, s46, 0x8000
	v_lshl_add_u64 v[254:255], v[138:139], 0, s[12:13]
	global_load_lds_dwordx4 v[254:255], off
	ds_read_b128 v[218:221], v64 offset:34816
	v_mfma_f32_16x16x32_bf16 v[20:23], v[230:233], v[242:245], v[20:23]
	v_mfma_f32_16x16x32_bf16 v[4:7], v[230:233], v[246:249], v[4:7]
	ds_read_b128 v[230:233], v64 offset:36864
	v_mfma_f32_16x16x32_bf16 v[16:19], v[234:237], v[242:245], v[16:19]
	v_mfma_f32_16x16x32_bf16 v[0:3], v[234:237], v[246:249], v[0:3]
	s_add_i32 m0, s46, 0xa000
	v_lshl_add_u64 v[254:255], v[140:141], 0, s[12:13]
	global_load_lds_dwordx4 v[254:255], off
	s_add_i32 s3, s3, 1
	s_cmpk_lg_i32 s12, 0x400
	ds_read_b128 v[234:237], v64 offset:38912
	ds_read_b128 v[242:245], v238 offset:4096
	ds_read_b128 v[246:249], v238 offset:6144
	s_waitcnt lgkmcnt(2)
	v_mfma_f32_16x16x32_bf16 v[60:63], v[214:217], v[222:225], v[60:63]
	v_mfma_f32_16x16x32_bf16 v[44:47], v[214:217], v[226:229], v[44:47]
	v_mfma_f32_16x16x32_bf16 v[56:59], v[218:221], v[222:225], v[56:59]
	v_mfma_f32_16x16x32_bf16 v[40:43], v[218:221], v[226:229], v[40:43]
	v_mfma_f32_16x16x32_bf16 v[52:55], v[230:233], v[222:225], v[52:55]
	v_mfma_f32_16x16x32_bf16 v[36:39], v[230:233], v[226:229], v[36:39]
	v_mfma_f32_16x16x32_bf16 v[48:51], v[234:237], v[222:225], v[48:51]
	v_mfma_f32_16x16x32_bf16 v[32:35], v[234:237], v[226:229], v[32:35]
	s_cbranch_scc0 .Lg3l_gemm1
	s_waitcnt vmcnt(6) lgkmcnt(0)
	s_branch .Lg3j_gemm1
.Lg3l_gemm1:
	s_waitcnt lgkmcnt(0)
.Lg3j_gemm1:
	v_mfma_f32_16x16x32_bf16 v[28:31], v[214:217], v[242:245], v[28:31]
	s_barrier
	v_mfma_f32_16x16x32_bf16 v[12:15], v[214:217], v[246:249], v[12:15]
	v_mfma_f32_16x16x32_bf16 v[24:27], v[218:221], v[242:245], v[24:27]
	v_mfma_f32_16x16x32_bf16 v[8:11], v[218:221], v[246:249], v[8:11]
	v_mfma_f32_16x16x32_bf16 v[20:23], v[230:233], v[242:245], v[20:23]
	v_mfma_f32_16x16x32_bf16 v[4:7], v[230:233], v[246:249], v[4:7]
	v_mfma_f32_16x16x32_bf16 v[16:19], v[234:237], v[242:245], v[16:19]
	v_mfma_f32_16x16x32_bf16 v[0:3], v[234:237], v[246:249], v[0:3]
	s_cbranch_scc0 .LBB0_1497

.LBB0_1530:
	s_and_b32 s8, s16, 7
	s_mul_i32 s8, s8, 0x142000
	s_add_i32 s8, s19, s8
	s_lshl_b32 s26, s8, 1
	s_and_b32 s8, s20, 0xffffff00
	s_ashr_i32 s9, s8, 31
	s_lshl_b64 s[10:11], s[8:9], 11
	s_and_b32 s8, s68, 7
	v_mov_b32_e32 v32, v198
	s_or_b32 s23, s8, s69
	s_lshl_b32 s8, s68, 5
	s_and_b32 s8, s8, 0xffffff00
	v_ashrrev_i32_e32 v33, 6, v32
	v_bfe_u32 v0, v32, 3, 3
	s_mul_i32 s9, s23, 0x284000
	v_lshl_or_b32 v0, v33, 3, v0
	s_add_u32 s12, s0, s9
	v_lshrrev_b32_e32 v35, 1, v0
	s_addc_u32 s13, s1, 0
	v_xor_b32_e32 v6, v35, v32
	s_ashr_i32 s9, s8, 31
	v_mov_b64_e32 v[2:3], s[12:13]
	v_lshlrev_b32_e32 v6, 4, v6
	v_lshl_add_u32 v146, v33, 10, 0
	s_lshl_b64 s[24:25], s[8:9], 11
	v_mad_i64_i32 v[4:5], s[12:13], v0, s22, v[2:3]
	v_and_b32_e32 v128, 0x70, v6
	v_readfirstlane_b32 s9, v146
	v_lshl_add_u64 v[4:5], v[4:5], 0, v[128:129]
	s_mov_b32 m0, s9
	v_add_u32_e32 v6, 64, v0
	global_load_lds_dwordx4 v[4:5], off
	v_add_u32_e32 v4, 0x2000, v146
	v_mad_i64_i32 v[8:9], s[12:13], v6, s22, v[2:3]
	v_add_u32_e32 v10, 0x80, v0
	v_readfirstlane_b32 s9, v4
	v_add_u32_e32 v4, 0x4000, v146
	v_lshl_add_u64 v[8:9], v[8:9], 0, v[128:129]
	v_mad_i64_i32 v[12:13], s[12:13], v10, s22, v[2:3]
	v_add_u32_e32 v14, 0xc0, v0
	s_mov_b32 m0, s9
	v_readfirstlane_b32 s9, v4
	v_add_u32_e32 v4, 0x6000, v146
	v_lshl_add_u64 v[12:13], v[12:13], 0, v[128:129]
	v_mad_i64_i32 v[2:3], s[12:13], v14, s22, v[2:3]
	global_load_lds_dwordx4 v[8:9], off
	s_mov_b32 m0, s9
	v_readfirstlane_b32 s9, v4
	s_add_u32 s24, s14, s24
	v_ashrrev_i32_e32 v1, 31, v0
	v_lshl_add_u64 v[2:3], v[2:3], 0, v[128:129]
	global_load_lds_dwordx4 v[12:13], off
	s_mov_b32 m0, s9
	s_addc_u32 s25, s15, s25
	v_ashrrev_i32_e32 v7, 31, v6
	v_lshlrev_b64 v[16:17], 11, v[0:1]
	global_load_lds_dwordx4 v[2:3], off
	v_add_u32_e32 v2, 0x8000, v146
	v_ashrrev_i32_e32 v11, 31, v10
	v_lshl_add_u64 v[18:19], s[24:25], 0, v[16:17]
	v_lshlrev_b64 v[20:21], 11, v[6:7]
	v_readfirstlane_b32 s9, v2
	v_add_u32_e32 v2, 0xa000, v146
	v_ashrrev_i32_e32 v15, 31, v14
	v_lshl_add_u64 v[18:19], v[18:19], 0, v[128:129]
	v_lshl_add_u64 v[22:23], s[24:25], 0, v[20:21]
	v_lshlrev_b64 v[24:25], 11, v[10:11]
	s_mov_b32 m0, s9
	v_readfirstlane_b32 s9, v2
	v_add_u32_e32 v2, 0xc000, v146
	v_lshl_add_u64 v[22:23], v[22:23], 0, v[128:129]
	v_lshl_add_u64 v[26:27], s[24:25], 0, v[24:25]
	v_lshlrev_b64 v[28:29], 11, v[14:15]
	global_load_lds_dwordx4 v[18:19], off
	s_mov_b32 m0, s9
	v_readfirstlane_b32 s9, v2
	v_add_u32_e32 v2, 0xe000, v146
	v_lshl_add_u64 v[26:27], v[26:27], 0, v[128:129]
	v_lshl_add_u64 v[30:31], s[24:25], 0, v[28:29]
	global_load_lds_dwordx4 v[22:23], off
	s_mov_b32 m0, s9
	v_readfirstlane_b32 s9, v2
	v_lshl_add_u64 v[30:31], v[30:31], 0, v[128:129]
	global_load_lds_dwordx4 v[26:27], off
	s_mov_b32 m0, s9
	v_lshrrev_b32_e32 v2, 30, v33
	global_load_lds_dwordx4 v[30:31], off
	v_add_u32_e32 v2, v33, v2
	v_bfe_u32 v1, v32, 4, 2
	v_bfe_u32 v7, v32, 1, 3
	v_ashrrev_i32_e32 v2, 2, v2
	v_mul_i32_i24_e32 v3, 4, v2
	v_lshlrev_b32_e32 v149, 14, v2
	v_xor_b32_e32 v2, v1, v7
	v_bitop3_b32 v1, v1, v7, 4 bitop3:0x36
	v_lshlrev_b32_e32 v151, 4, v1
	v_bitop3_b32 v1, v35, 7, v32 bitop3:0x48
	v_lshlrev_b32_e32 v128, 4, v1
	v_mad_i64_i32 v[0:1], s[12:13], v0, s22, v[128:129]
	s_add_u32 s12, s17, s26
	s_addc_u32 s13, s18, 0
	v_lshl_add_u64 v[130:131], s[12:13], 0, v[0:1]
	v_mad_i64_i32 v[0:1], s[24:25], v6, s22, v[128:129]
	v_lshl_add_u64 v[132:133], s[12:13], 0, v[0:1]
	v_mad_i64_i32 v[0:1], s[24:25], v10, s22, v[128:129]
	v_lshl_add_u64 v[134:135], s[12:13], 0, v[0:1]
	v_mad_i64_i32 v[0:1], s[24:25], v14, s22, v[128:129]
	v_lshl_add_u64 v[136:137], s[12:13], 0, v[0:1]
	v_lshl_add_u64 v[0:1], s[10:11], 0, v[16:17]
	v_or_b32_e32 v0, v0, v128
	v_lshl_add_u64 v[138:139], s[4:5], 0, v[0:1]
	v_lshl_add_u64 v[0:1], s[10:11], 0, v[20:21]
	v_or_b32_e32 v0, v0, v128
	v_lshl_add_u64 v[140:141], s[4:5], 0, v[0:1]
	v_lshl_add_u64 v[0:1], s[10:11], 0, v[24:25]
	v_or_b32_e32 v0, v0, v128
	v_lshl_add_u64 v[142:143], s[4:5], 0, v[0:1]
	v_lshl_add_u64 v[0:1], s[10:11], 0, v[28:29]
	v_and_b32_e32 v34, 15, v32
	v_sub_u32_e32 v3, v33, v3
	v_or_b32_e32 v0, v0, v128
	v_lshlrev_b32_e32 v147, 13, v3
	v_lshlrev_b32_e32 v148, 7, v34
	v_lshlrev_b32_e32 v150, 4, v2
	v_lshl_add_u64 v[144:145], s[4:5], 0, v[0:1]
	s_mov_b32 s9, 0
	s_mov_b64 s[10:11], 0
	v_mov_b32_e32 v20, 0
	v_mov_b32_e32 v21, v129
	v_mov_b32_e32 v22, v129
	v_mov_b32_e32 v23, v129
	v_mov_b32_e32 v0, 0
	v_mov_b32_e32 v1, v129
	v_mov_b32_e32 v2, v129
	v_mov_b32_e32 v3, v129
	v_mov_b32_e32 v4, 0
	v_mov_b32_e32 v5, v129
	v_mov_b32_e32 v6, v129
	v_mov_b32_e32 v7, v129
	v_mov_b32_e32 v8, 0
	v_mov_b32_e32 v9, v129
	v_mov_b32_e32 v10, v129
	v_mov_b32_e32 v11, v129
	v_mov_b32_e32 v12, 0
	v_mov_b32_e32 v13, v129
	v_mov_b32_e32 v14, v129
	v_mov_b32_e32 v15, v129
	v_mov_b32_e32 v16, 0
	v_mov_b32_e32 v17, v129
	v_mov_b32_e32 v18, v129
	v_mov_b32_e32 v19, v129
	v_mov_b32_e32 v24, 0
	v_mov_b32_e32 v25, v129
	v_mov_b32_e32 v26, v129
	v_mov_b32_e32 v27, v129
	v_mov_b32_e32 v28, 0
	v_mov_b32_e32 v29, v129
	v_mov_b32_e32 v30, v129
	v_mov_b32_e32 v31, v129
	v_mov_b32_e32 v32, 0
	v_mov_b32_e32 v33, v129
	v_mov_b32_e32 v34, v129
	v_mov_b32_e32 v35, v129
	v_mov_b32_e32 v36, 0
	v_mov_b32_e32 v37, v129
	v_mov_b32_e32 v38, v129
	v_mov_b32_e32 v39, v129
	v_mov_b32_e32 v40, 0
	v_mov_b32_e32 v41, v129
	v_mov_b32_e32 v42, v129
	v_mov_b32_e32 v43, v129
	v_mov_b32_e32 v44, 0
	v_mov_b32_e32 v45, v129
	v_mov_b32_e32 v46, v129
	v_mov_b32_e32 v47, v129
	v_mov_b32_e32 v48, 0
	v_mov_b32_e32 v49, v129
	v_mov_b32_e32 v50, v129
	v_mov_b32_e32 v51, v129
	v_mov_b32_e32 v52, 0
	v_mov_b32_e32 v53, v129
	v_mov_b32_e32 v54, v129
	v_mov_b32_e32 v55, v129
	v_mov_b32_e32 v56, 0
	v_mov_b32_e32 v57, v129
	v_mov_b32_e32 v58, v129
	v_mov_b32_e32 v59, v129
	v_mov_b32_e32 v60, 0
	v_mov_b32_e32 v61, v129
	v_mov_b32_e32 v62, v129
	v_mov_b32_e32 v63, v129
	v_mov_b32_e32 v64, 0
	v_mov_b32_e32 v65, v129
	v_mov_b32_e32 v66, v129
	v_mov_b32_e32 v67, v129
	v_mov_b32_e32 v68, 0
	v_mov_b32_e32 v69, v129
	v_mov_b32_e32 v70, v129
	v_mov_b32_e32 v71, v129
	v_mov_b32_e32 v72, 0
	v_mov_b32_e32 v73, v129
	v_mov_b32_e32 v74, v129
	v_mov_b32_e32 v75, v129
	v_mov_b32_e32 v76, 0
	v_mov_b32_e32 v77, v129
	v_mov_b32_e32 v78, v129
	v_mov_b32_e32 v79, v129
	v_mov_b32_e32 v80, 0
	v_mov_b32_e32 v81, v129
	v_mov_b32_e32 v82, v129
	v_mov_b32_e32 v83, v129
	v_mov_b32_e32 v84, 0
	v_mov_b32_e32 v85, v129
	v_mov_b32_e32 v86, v129
	v_mov_b32_e32 v87, v129
	v_mov_b32_e32 v88, 0
	v_mov_b32_e32 v89, v129
	v_mov_b32_e32 v90, v129
	v_mov_b32_e32 v91, v129
	v_mov_b32_e32 v92, 0
	v_mov_b32_e32 v93, v129
	v_mov_b32_e32 v94, v129
	v_mov_b32_e32 v95, v129
	v_mov_b32_e32 v96, 0
	v_mov_b32_e32 v97, v129
	v_mov_b32_e32 v98, v129
	v_mov_b32_e32 v99, v129
	v_mov_b32_e32 v100, 0
	v_mov_b32_e32 v101, v129
	v_mov_b32_e32 v102, v129
	v_mov_b32_e32 v103, v129
	v_mov_b32_e32 v104, 0
	v_mov_b32_e32 v105, v129
	v_mov_b32_e32 v106, v129
	v_mov_b32_e32 v107, v129
	v_mov_b32_e32 v108, 0
	v_mov_b32_e32 v109, v129
	v_mov_b32_e32 v110, v129
	v_mov_b32_e32 v111, v129
	v_mov_b32_e32 v112, 0
	v_mov_b32_e32 v113, v129
	v_mov_b32_e32 v114, v129
	v_mov_b32_e32 v115, v129
	v_mov_b32_e32 v116, 0
	v_mov_b32_e32 v117, v129
	v_mov_b32_e32 v118, v129
	v_mov_b32_e32 v119, v129
	v_mov_b32_e32 v120, 0
	v_mov_b32_e32 v121, v129
	v_mov_b32_e32 v122, v129
	v_mov_b32_e32 v123, v129
	v_mov_b32_e32 v124, 0
	v_mov_b32_e32 v125, v129
	v_mov_b32_e32 v126, v129
	v_mov_b32_e32 v127, v129
	s_waitcnt vmcnt(0) lgkmcnt(0)
	s_barrier
	s_branch .LBB0_1532
